# embed
# speedup vs baseline: 1.0079x; 1.0051x over previous
; #define PG8_STAGE(bufoff, gbase, voff) do { _Pragma("unroll") for (int _i = 0; _i < 2; ++_i) \
;         __builtin_amdgcn_global_load_lds((const unsigned*)((const char*)(gbase) + (voff)[_i]), (LAS unsigned*)(lds + (bufoff) + ldsw + _i * 8192), 16, 0, 0); } while (0)
; #define PG8_LDA(dst, b, h) do { _Pragma("unroll") for (int m = 0; m < 4; ++m) _Pragma("unroll") for (int k = 0; k < 2; ++k) dst[m][k] = *(const LAS bf16x8*)(lds + PG8_SA(b, h) + aoff + m * 2048 + k * 1024); } while (0)
; #define PG8_LDB(dst, b, h) do { _Pragma("unroll") for (int n = 0; n < 2; ++n) _Pragma("unroll") for (int k = 0; k < 2; ++k) dst[n][k] = *(const LAS bf16x8*)(lds + PG8_SB(b, h) + boff + n * 2048 + k * 1024); } while (0)
; #define PG8_MMA(ai, bj, At, Bt) do { __builtin_amdgcn_s_setprio(1); _Pragma("unroll") for (int m = 0; m < 4; ++m) _Pragma("unroll") for (int n = 0; n < 2; ++n) _Pragma("unroll") for (int k = 0; k < 2; ++k) \
;         acc[ai][bj][m][n] = __builtin_amdgcn_mfma_f32_16x16x32_bf16(Bt[n][k], At[m][k], acc[ai][bj][m][n], 0, 0, 0); __builtin_amdgcn_s_setprio(0); } while (0)
; #define PG8_WAIT_L(n) asm volatile("s_waitcnt lgkmcnt(" #n ")" ::: "memory")
; #define PG8_BAR __builtin_amdgcn_s_barrier()
; #define PG8_SCHED __builtin_amdgcn_sched_barrier(0)
; template <class Epi, class Job>
; __device__ __forceinline__ void gemm_phase(LAS unsigned char* lds, const Job& S, const Epi& E) {
;     ...
;             PG8_LDB(B0, 0, 0); PG8_SCHED; PG8_LDA(At, 0, 0); PG8_STAGE(PG8_SA(1, 1), a1 + hstepA, voffA);
;             PG8_WAIT_L(8); PG8_BAR; PG8_WAIT_L(0); PG8_MMA(0, 0, At, B0); PG8_BAR; PG8_SCHED;
;             PG8_LDB(B1, 0, 1); PG8_STAGE(PG8_SB(0, 0), b2, voffB);
;             PG8_BAR; PG8_WAIT_L(0); PG8_MMA(0, 1, At, B1); PG8_BAR;
;             PG8_LDA(At, 0, 1); PG8_STAGE(PG8_SA(0, 0), a2, voffA);
;     ...
;         for (int a = 0; a < 2; ++a)
; #pragma unroll
;             for (int b = 0; b < 2; ++b)
; #pragma unroll
;                 for (int m = 0; m < 4; ++m)
; #pragma unroll
;                     for (int n = 0; n < 2; ++n) acc[a][b][m][n] = (f32x4){0.f, 0.f, 0.f, 0.f};
.LBB0_185:
	s_add_u32 s28, s28, 0x100080
	s_addc_u32 s29, s29, 0
	s_add_u32 s27, s36, 0x100
	v_mov_b32_e32 v0, 0
	s_addc_u32 s67, s37, 0
	s_mov_b32 s68, -2
	v_mov_b32_e32 v1, v0
	v_mov_b32_e32 v2, v0
	v_mov_b32_e32 v3, v0
	v_mov_b32_e32 v4, v0
	v_mov_b32_e32 v5, v0
	v_mov_b32_e32 v6, v0
	v_mov_b32_e32 v7, v0
	v_mov_b32_e32 v8, v0
	v_mov_b32_e32 v9, v0
	v_mov_b32_e32 v10, v0
	v_mov_b32_e32 v11, v0
	v_mov_b32_e32 v16, v0
	v_mov_b32_e32 v17, v0
	v_mov_b32_e32 v18, v0
	v_mov_b32_e32 v19, v0
	v_mov_b32_e32 v24, v0
	v_mov_b32_e32 v25, v0
	v_mov_b32_e32 v26, v0
	v_mov_b32_e32 v27, v0
	v_mov_b32_e32 v32, v0
	v_mov_b32_e32 v33, v0
	v_mov_b32_e32 v34, v0
	v_mov_b32_e32 v35, v0
	v_mov_b32_e32 v40, v0
	v_mov_b32_e32 v41, v0
	v_mov_b32_e32 v42, v0
	v_mov_b32_e32 v43, v0
	v_mov_b32_e32 v48, v0
	v_mov_b32_e32 v49, v0
	v_mov_b32_e32 v50, v0
	v_mov_b32_e32 v51, v0
	v_mov_b32_e32 v12, v0
	v_mov_b32_e32 v13, v0
	v_mov_b32_e32 v14, v0
	v_mov_b32_e32 v15, v0
	v_mov_b32_e32 v20, v0
	v_mov_b32_e32 v21, v0
	v_mov_b32_e32 v22, v0
	v_mov_b32_e32 v23, v0
	v_mov_b32_e32 v28, v0
	v_mov_b32_e32 v29, v0
	v_mov_b32_e32 v30, v0
	v_mov_b32_e32 v31, v0
	v_mov_b32_e32 v36, v0
	v_mov_b32_e32 v37, v0
	v_mov_b32_e32 v38, v0
	v_mov_b32_e32 v39, v0
	v_mov_b32_e32 v44, v0
	v_mov_b32_e32 v45, v0
	v_mov_b32_e32 v46, v0
	v_mov_b32_e32 v47, v0
	v_mov_b32_e32 v52, v0
	v_mov_b32_e32 v53, v0
	v_mov_b32_e32 v54, v0
	v_mov_b32_e32 v55, v0
	v_mov_b32_e32 v56, v0
	v_mov_b32_e32 v57, v0
	v_mov_b32_e32 v58, v0
	v_mov_b32_e32 v59, v0
	v_mov_b32_e32 v60, v0
	v_mov_b32_e32 v61, v0
	v_mov_b32_e32 v62, v0
	v_mov_b32_e32 v63, v0
	v_mov_b32_e32 v64, v0
	v_mov_b32_e32 v65, v0
	v_mov_b32_e32 v66, v0
	v_mov_b32_e32 v67, v0
	v_mov_b32_e32 v68, v0
	v_mov_b32_e32 v69, v0
	v_mov_b32_e32 v70, v0
	v_mov_b32_e32 v71, v0
	v_mov_b32_e32 v72, v0
	v_mov_b32_e32 v73, v0
	v_mov_b32_e32 v74, v0
	v_mov_b32_e32 v75, v0
	v_mov_b32_e32 v80, v0
	v_mov_b32_e32 v81, v0
	v_mov_b32_e32 v82, v0
	v_mov_b32_e32 v83, v0
	v_mov_b32_e32 v88, v0
	v_mov_b32_e32 v89, v0
	v_mov_b32_e32 v90, v0
	v_mov_b32_e32 v91, v0
	v_mov_b32_e32 v96, v0
	v_mov_b32_e32 v97, v0
	v_mov_b32_e32 v98, v0
	v_mov_b32_e32 v99, v0
	v_mov_b32_e32 v108, v0
	v_mov_b32_e32 v109, v0
	v_mov_b32_e32 v110, v0
	v_mov_b32_e32 v111, v0
	v_mov_b32_e32 v116, v0
	v_mov_b32_e32 v117, v0
	v_mov_b32_e32 v118, v0
	v_mov_b32_e32 v119, v0
	v_mov_b32_e32 v76, v0
	v_mov_b32_e32 v77, v0
	v_mov_b32_e32 v78, v0
	v_mov_b32_e32 v79, v0
	v_mov_b32_e32 v84, v0
	v_mov_b32_e32 v85, v0
	v_mov_b32_e32 v86, v0
	v_mov_b32_e32 v87, v0
	v_mov_b32_e32 v92, v0
	v_mov_b32_e32 v93, v0
	v_mov_b32_e32 v94, v0
	v_mov_b32_e32 v95, v0
	v_mov_b32_e32 v100, v0
	v_mov_b32_e32 v101, v0
	v_mov_b32_e32 v102, v0
	v_mov_b32_e32 v103, v0
	v_mov_b32_e32 v104, v0
	v_mov_b32_e32 v105, v0
	v_mov_b32_e32 v106, v0
	v_mov_b32_e32 v107, v0
	v_mov_b32_e32 v112, v0
	v_mov_b32_e32 v113, v0
	v_mov_b32_e32 v114, v0
	v_mov_b32_e32 v115, v0
	v_mov_b32_e32 v120, v0
	v_mov_b32_e32 v121, v0
	v_mov_b32_e32 v122, v0
	v_mov_b32_e32 v123, v0
	v_mov_b32_e32 v124, v0
	v_mov_b32_e32 v125, v0
	v_mov_b32_e32 v126, v0
	v_mov_b32_e32 v127, v0
	ds_read_b128 v[158:161], v154
	ds_read_b128 v[174:177], v154 offset:1024
	ds_read_b128 v[178:181], v154 offset:2048
	ds_read_b128 v[182:185], v154 offset:3072
	ds_read_b128 v[186:189], v155
	ds_read_b128 v[194:197], v155 offset:2048
	ds_read_b128 v[202:205], v155 offset:4096
	ds_read_b128 v[210:213], v155 offset:6144
.LBB0_186:
	s_add_u32 s36, s28, 0xfff00080
	s_addc_u32 s37, s29, -1
	s_cmp_eq_u32 s68, 60
	s_cselect_b32 s47, s23, s37
	s_cselect_b32 s46, s22, s36
	s_cselect_b32 s37, s25, s67
	s_cselect_b32 s36, s24, s27
	s_add_i32 m0, s52, 0xc000
	ds_read_b128 v[190:193], v155 offset:1024
	ds_read_b128 v[198:201], v155 offset:3072
	ds_read_b128 v[206:209], v155 offset:5120
	ds_read_b128 v[214:217], v155 offset:7168
	global_load_lds_dwordx4 v144, s[28:29]
	s_add_i32 m0, s52, 0xe000
	s_nop 0
	global_load_lds_dwordx4 v146, s[28:29]
	s_waitcnt lgkmcnt(8)
	s_barrier
	s_waitcnt lgkmcnt(0)
	s_setprio 1
	v_mfma_f32_16x16x32_bf16 v[124:127], v[158:161], v[186:189], v[124:127]
	ds_read_b128 v[218:221], v156
	v_mfma_f32_16x16x32_bf16 v[120:123], v[178:181], v[186:189], v[120:123]
	v_mfma_f32_16x16x32_bf16 v[112:115], v[158:161], v[194:197], v[112:115]
	ds_read_b128 v[222:225], v156 offset:1024
	v_mfma_f32_16x16x32_bf16 v[104:107], v[178:181], v[194:197], v[104:107]
	v_mfma_f32_16x16x32_bf16 v[100:103], v[158:161], v[202:205], v[100:103]
	ds_read_b128 v[226:229], v156 offset:2048
	v_mfma_f32_16x16x32_bf16 v[92:95], v[178:181], v[202:205], v[92:95]
	v_mfma_f32_16x16x32_bf16 v[84:87], v[158:161], v[210:213], v[84:87]
	ds_read_b128 v[230:233], v156 offset:3072
	v_mfma_f32_16x16x32_bf16 v[76:79], v[178:181], v[210:213], v[76:79]
	v_mfma_f32_16x16x32_bf16 v[124:127], v[174:177], v[190:193], v[124:127]
	v_mfma_f32_16x16x32_bf16 v[120:123], v[182:185], v[190:193], v[120:123]
	v_mfma_f32_16x16x32_bf16 v[112:115], v[174:177], v[198:201], v[112:115]
	v_mfma_f32_16x16x32_bf16 v[104:107], v[182:185], v[198:201], v[104:107]
	v_mfma_f32_16x16x32_bf16 v[100:103], v[174:177], v[206:209], v[100:103]
	v_mfma_f32_16x16x32_bf16 v[92:95], v[182:185], v[206:209], v[92:95]
	v_mfma_f32_16x16x32_bf16 v[84:87], v[174:177], v[214:217], v[84:87]
	v_mfma_f32_16x16x32_bf16 v[76:79], v[182:185], v[214:217], v[76:79]
	s_setprio 0
	s_barrier
	s_add_i32 s69, s60, s49
	s_mov_b32 m0, s69
	s_nop 0
	global_load_lds_dwordx4 v136, s[36:37]
	s_add_i32 m0, s69, 0x2000
	s_nop 0
	global_load_lds_dwordx4 v140, s[36:37]
	s_barrier
; #define PG8_STAGE(bufoff, gbase, voff) do { _Pragma("unroll") for (int _i = 0; _i < 2; ++_i) \
;         __builtin_amdgcn_global_load_lds((const unsigned*)((const char*)(gbase) + (voff)[_i]), (LAS unsigned*)(lds + (bufoff) + ldsw + _i * 8192), 16, 0, 0); } while (0)
; #define PG8_LDA(dst, b, h) do { _Pragma("unroll") for (int m = 0; m < 4; ++m) _Pragma("unroll") for (int k = 0; k < 2; ++k) dst[m][k] = *(const LAS bf16x8*)(lds + PG8_SA(b, h) + aoff + m * 2048 + k * 1024); } while (0)
; #define PG8_LDB(dst, b, h) do { _Pragma("unroll") for (int n = 0; n < 2; ++n) _Pragma("unroll") for (int k = 0; k < 2; ++k) dst[n][k] = *(const LAS bf16x8*)(lds + PG8_SB(b, h) + boff + n * 2048 + k * 1024); } while (0)
; #define PG8_MMA(ai, bj, At, Bt) do { __builtin_amdgcn_s_setprio(1); _Pragma("unroll") for (int m = 0; m < 4; ++m) _Pragma("unroll") for (int n = 0; n < 2; ++n) _Pragma("unroll") for (int k = 0; k < 2; ++k) \
;         acc[ai][bj][m][n] = __builtin_amdgcn_mfma_f32_16x16x32_bf16(Bt[n][k], At[m][k], acc[ai][bj][m][n], 0, 0, 0); __builtin_amdgcn_s_setprio(0); } while (0)
; #define PG8_WAIT_V(n) asm volatile("s_waitcnt vmcnt(" #n ")" ::: "memory")
; #define PG8_WAIT_L(n) asm volatile("s_waitcnt lgkmcnt(" #n ")" ::: "memory")
; #define PG8_BAR __builtin_amdgcn_s_barrier()
; #define PG8_SCHED __builtin_amdgcn_sched_barrier(0)
; template <class Epi, class Job>
; __device__ __forceinline__ void gemm_phase(LAS unsigned char* lds, const Job& S, const Epi& E) {
;     ...
;             PG8_BAR; PG8_WAIT_L(0); PG8_MMA(0, 1, At, B1); PG8_BAR;
;             PG8_LDA(At, 0, 1); PG8_STAGE(PG8_SA(0, 0), a2, voffA);
;             PG8_BAR; PG8_WAIT_L(0); PG8_MMA(1, 0, At, B0); PG8_BAR; PG8_SCHED;
;             PG8_STAGE(PG8_SB(0, 1), b2 + hstepB, voffB);
;             PG8_WAIT_V(6); PG8_BAR; PG8_MMA(1, 1, At, B1); PG8_BAR;
;             PG8_LDB(B0, 1, 0); PG8_SCHED; PG8_LDA(At, 1, 0); PG8_STAGE(PG8_SA(0, 1), a2 + hstepA, voffA);
;             PG8_WAIT_L(8); PG8_BAR; PG8_WAIT_L(0); PG8_MMA(0, 0, At, B0); PG8_BAR; PG8_SCHED;
	s_waitcnt lgkmcnt(0)
	s_setprio 1
	v_mfma_f32_16x16x32_bf16 v[116:119], v[218:221], v[186:189], v[116:119]
	v_mfma_f32_16x16x32_bf16 v[108:111], v[226:229], v[186:189], v[108:111]
	v_mfma_f32_16x16x32_bf16 v[96:99], v[218:221], v[194:197], v[96:99]
	v_mfma_f32_16x16x32_bf16 v[88:91], v[226:229], v[194:197], v[88:91]
	v_mfma_f32_16x16x32_bf16 v[80:83], v[218:221], v[202:205], v[80:83]
	v_mfma_f32_16x16x32_bf16 v[72:75], v[226:229], v[202:205], v[72:75]
	v_mfma_f32_16x16x32_bf16 v[68:71], v[218:221], v[210:213], v[68:71]
	v_mfma_f32_16x16x32_bf16 v[64:67], v[226:229], v[210:213], v[64:67]
	v_mfma_f32_16x16x32_bf16 v[116:119], v[222:225], v[190:193], v[116:119]
	ds_read_b128 v[186:189], v155 offset:16384
	v_mfma_f32_16x16x32_bf16 v[108:111], v[230:233], v[190:193], v[108:111]
	v_mfma_f32_16x16x32_bf16 v[96:99], v[222:225], v[198:201], v[96:99]
	ds_read_b128 v[194:197], v155 offset:18432
	v_mfma_f32_16x16x32_bf16 v[88:91], v[230:233], v[198:201], v[88:91]
	v_mfma_f32_16x16x32_bf16 v[80:83], v[222:225], v[206:209], v[80:83]
	ds_read_b128 v[202:205], v155 offset:20480
	v_mfma_f32_16x16x32_bf16 v[72:75], v[230:233], v[206:209], v[72:75]
	v_mfma_f32_16x16x32_bf16 v[68:71], v[222:225], v[214:217], v[68:71]
	ds_read_b128 v[210:213], v155 offset:22528
	v_mfma_f32_16x16x32_bf16 v[64:67], v[230:233], v[214:217], v[64:67]
	s_setprio 0
	s_mov_b32 m0, s52
	s_mov_b64 s[100:101], s[46:47]
	s_barrier
	ds_read_b128 v[190:193], v155 offset:17408
	ds_read_b128 v[198:201], v155 offset:19456
	ds_read_b128 v[206:209], v155 offset:21504
	ds_read_b128 v[214:217], v155 offset:23552
	global_load_lds_dwordx4 v134, s[46:47]
	s_mov_b32 m0, s53
	s_nop 0
	global_load_lds_dwordx4 v138, s[46:47]
	s_waitcnt vmcnt(8)
	s_barrier
	s_waitcnt lgkmcnt(0)
	s_setprio 1
	v_mfma_f32_16x16x32_bf16 v[60:63], v[158:161], v[186:189], v[60:63]
	v_mfma_f32_16x16x32_bf16 v[56:59], v[178:181], v[186:189], v[56:59]
	v_mfma_f32_16x16x32_bf16 v[52:55], v[158:161], v[194:197], v[52:55]
	v_mfma_f32_16x16x32_bf16 v[44:47], v[178:181], v[194:197], v[44:47]
	v_mfma_f32_16x16x32_bf16 v[36:39], v[158:161], v[202:205], v[36:39]
	v_mfma_f32_16x16x32_bf16 v[28:31], v[178:181], v[202:205], v[28:31]
	v_mfma_f32_16x16x32_bf16 v[20:23], v[158:161], v[210:213], v[20:23]
	v_mfma_f32_16x16x32_bf16 v[12:15], v[178:181], v[210:213], v[12:15]
	v_mfma_f32_16x16x32_bf16 v[60:63], v[174:177], v[190:193], v[60:63]
	v_mfma_f32_16x16x32_bf16 v[56:59], v[182:185], v[190:193], v[56:59]
	v_mfma_f32_16x16x32_bf16 v[52:55], v[174:177], v[198:201], v[52:55]
	v_mfma_f32_16x16x32_bf16 v[44:47], v[182:185], v[198:201], v[44:47]
	v_mfma_f32_16x16x32_bf16 v[36:39], v[174:177], v[206:209], v[36:39]
	v_mfma_f32_16x16x32_bf16 v[28:31], v[182:185], v[206:209], v[28:31]
	v_mfma_f32_16x16x32_bf16 v[20:23], v[174:177], v[214:217], v[20:23]
	v_mfma_f32_16x16x32_bf16 v[12:15], v[182:185], v[214:217], v[12:15]
	s_setprio 0
	s_barrier
	s_add_u32 s70, s36, 0x100000
	s_addc_u32 s71, s37, 0
	s_add_i32 s69, s61, s49
	s_mov_b32 m0, s69
	s_nop 0
	global_load_lds_dwordx4 v136, s[70:71]
	s_add_i32 m0, s69, 0x2000
	s_nop 0
	global_load_lds_dwordx4 v140, s[70:71]
	s_waitcnt vmcnt(6)
	s_barrier
	s_setprio 1
	v_add_u32_e32 v157, 0x18000, v153
	v_mfma_f32_16x16x32_bf16 v[48:51], v[218:221], v[186:189], v[48:51]
	ds_read_b128 v[158:161], v157
	v_mfma_f32_16x16x32_bf16 v[40:43], v[226:229], v[186:189], v[40:43]
	v_mfma_f32_16x16x32_bf16 v[32:35], v[218:221], v[194:197], v[32:35]
	ds_read_b128 v[174:177], v157 offset:1024
	v_mfma_f32_16x16x32_bf16 v[24:27], v[226:229], v[194:197], v[24:27]
	v_mfma_f32_16x16x32_bf16 v[16:19], v[218:221], v[202:205], v[16:19]
	ds_read_b128 v[178:181], v157 offset:2048
	v_mfma_f32_16x16x32_bf16 v[8:11], v[226:229], v[202:205], v[8:11]
	v_mfma_f32_16x16x32_bf16 v[4:7], v[218:221], v[210:213], v[4:7]
	ds_read_b128 v[182:185], v157 offset:3072
	v_mfma_f32_16x16x32_bf16 v[0:3], v[226:229], v[210:213], v[0:3]
	v_mfma_f32_16x16x32_bf16 v[48:51], v[222:225], v[190:193], v[48:51]
	ds_read_b128 v[186:189], v155 offset:32768
	v_mfma_f32_16x16x32_bf16 v[40:43], v[230:233], v[190:193], v[40:43]
	v_mfma_f32_16x16x32_bf16 v[32:35], v[222:225], v[198:201], v[32:35]
	ds_read_b128 v[194:197], v155 offset:34816
	v_mfma_f32_16x16x32_bf16 v[24:27], v[230:233], v[198:201], v[24:27]
	v_mfma_f32_16x16x32_bf16 v[16:19], v[222:225], v[206:209], v[16:19]
	ds_read_b128 v[202:205], v155 offset:36864
	v_mfma_f32_16x16x32_bf16 v[8:11], v[230:233], v[206:209], v[8:11]
	v_mfma_f32_16x16x32_bf16 v[4:7], v[222:225], v[214:217], v[4:7]
	ds_read_b128 v[210:213], v155 offset:38912
	v_mfma_f32_16x16x32_bf16 v[0:3], v[230:233], v[214:217], v[0:3]
	s_setprio 0
	s_add_i32 s69, 0, 0x18000
	v_add_u32_e32 v157, s69, v153
	s_barrier
	s_add_u32 s46, s46, 0x100000
	s_addc_u32 s47, s47, 0
	s_mov_b32 m0, s54
	ds_read_b128 v[190:193], v155 offset:33792
	ds_read_b128 v[198:201], v155 offset:35840
	ds_read_b128 v[206:209], v155 offset:37888
	ds_read_b128 v[214:217], v155 offset:39936
	global_load_lds_dwordx4 v134, s[46:47]
	s_mov_b32 m0, s55
	s_nop 0
	global_load_lds_dwordx4 v138, s[46:47]
	s_waitcnt lgkmcnt(8)
	s_barrier
; #define PG8_STAGE(bufoff, gbase, voff) do { _Pragma("unroll") for (int _i = 0; _i < 2; ++_i) \
;         __builtin_amdgcn_global_load_lds((const unsigned*)((const char*)(gbase) + (voff)[_i]), (LAS unsigned*)(lds + (bufoff) + ldsw + _i * 8192), 16, 0, 0); } while (0)
; #define PG8_LDA(dst, b, h) do { _Pragma("unroll") for (int m = 0; m < 4; ++m) _Pragma("unroll") for (int k = 0; k < 2; ++k) dst[m][k] = *(const LAS bf16x8*)(lds + PG8_SA(b, h) + aoff + m * 2048 + k * 1024); } while (0)
; #define PG8_LDB(dst, b, h) do { _Pragma("unroll") for (int n = 0; n < 2; ++n) _Pragma("unroll") for (int k = 0; k < 2; ++k) dst[n][k] = *(const LAS bf16x8*)(lds + PG8_SB(b, h) + boff + n * 2048 + k * 1024); } while (0)
; #define PG8_MMA(ai, bj, At, Bt) do { __builtin_amdgcn_s_setprio(1); _Pragma("unroll") for (int m = 0; m < 4; ++m) _Pragma("unroll") for (int n = 0; n < 2; ++n) _Pragma("unroll") for (int k = 0; k < 2; ++k) \
;         acc[ai][bj][m][n] = __builtin_amdgcn_mfma_f32_16x16x32_bf16(Bt[n][k], At[m][k], acc[ai][bj][m][n], 0, 0, 0); __builtin_amdgcn_s_setprio(0); } while (0)
;     __device__ __forceinline__ void operator()(const f32x4 (&acc)[2][2][4][2], const Unit& u, int wr, int wc, int fr, int fq) const {
;         const int row0 = u.orow + wr * 64 + fr;
;         bf16_t* base; size_t rstride, bjstride;
;         if (u.ocol < 6144) { const int sect = u.ocol >> 11, hh0 = (u.ocol & 2047) >> 7, b = u.orow >= SEQ ? 1 : 0;
;             base = qkv + (size_t)sect * MTOK * 2048 + ((size_t)(b * 16 + hh0) * SEQ + (row0 & (SEQ - 1))) * 128 + wc * 32 + 8 * fq; rstride = 128; bjstride = (size_t)SEQ * 128; }
;         else { base = proj2 + (size_t)row0 * NP2 + (u.ocol - 6144) + wc * 32 + 8 * fq; rstride = NP2; bjstride = HALF; }
; template <class Epi, class Job>
; __device__ __forceinline__ void gemm_phase(LAS unsigned char* lds, const Job& S, const Epi& E) {
;     ...
;             PG8_WAIT_L(8); PG8_BAR; PG8_WAIT_L(0); PG8_MMA(0, 0, At, B0); PG8_BAR; PG8_SCHED;
;             PG8_LDB(B1, 1, 1); PG8_STAGE(PG8_SB(1, 0), b3, voffB);
;             PG8_BAR; PG8_WAIT_L(0); PG8_MMA(0, 1, At, B1); PG8_BAR;
;             PG8_LDA(At, 1, 1); PG8_STAGE(PG8_SA(1, 0), a3, voffA);
;             PG8_BAR; PG8_WAIT_L(0); PG8_MMA(1, 0, At, B0); PG8_BAR; PG8_SCHED;
;             PG8_STAGE(PG8_SB(1, 1), b3 + hstepB, voffB);
;             PG8_WAIT_V(6); PG8_BAR; PG8_MMA(1, 1, At, B1); PG8_BAR;
	s_waitcnt lgkmcnt(0)
	s_setprio 1
	v_add_u32_e32 v157, 0x1c000, v153
	v_mfma_f32_16x16x32_bf16 v[124:127], v[158:161], v[186:189], v[124:127]
	ds_read_b128 v[218:221], v157
	v_mfma_f32_16x16x32_bf16 v[120:123], v[178:181], v[186:189], v[120:123]
	v_mfma_f32_16x16x32_bf16 v[112:115], v[158:161], v[194:197], v[112:115]
	ds_read_b128 v[222:225], v157 offset:1024
	v_mfma_f32_16x16x32_bf16 v[104:107], v[178:181], v[194:197], v[104:107]
	v_mfma_f32_16x16x32_bf16 v[100:103], v[158:161], v[202:205], v[100:103]
	ds_read_b128 v[226:229], v157 offset:2048
	v_mfma_f32_16x16x32_bf16 v[92:95], v[178:181], v[202:205], v[92:95]
	v_mfma_f32_16x16x32_bf16 v[84:87], v[158:161], v[210:213], v[84:87]
	ds_read_b128 v[230:233], v157 offset:3072
	v_mfma_f32_16x16x32_bf16 v[76:79], v[178:181], v[210:213], v[76:79]
	v_mfma_f32_16x16x32_bf16 v[124:127], v[174:177], v[190:193], v[124:127]
	v_mfma_f32_16x16x32_bf16 v[120:123], v[182:185], v[190:193], v[120:123]
	v_mfma_f32_16x16x32_bf16 v[112:115], v[174:177], v[198:201], v[112:115]
	v_mfma_f32_16x16x32_bf16 v[104:107], v[182:185], v[198:201], v[104:107]
	v_mfma_f32_16x16x32_bf16 v[100:103], v[174:177], v[206:209], v[100:103]
	v_mfma_f32_16x16x32_bf16 v[92:95], v[182:185], v[206:209], v[92:95]
	v_mfma_f32_16x16x32_bf16 v[84:87], v[174:177], v[214:217], v[84:87]
	v_mfma_f32_16x16x32_bf16 v[76:79], v[182:185], v[214:217], v[76:79]
	s_setprio 0
	s_barrier
	s_add_i32 s46, 0, 0x1c000
	s_add_i32 s47, s69, s49
	v_add_u32_e32 v157, s46, v153
	s_add_u32 s98, s36, s10
	s_addc_u32 s99, s37, s11
	s_mov_b32 m0, s47
	s_nop 0
	global_load_lds_dwordx4 v136, s[98:99]
	s_add_i32 m0, s47, 0x2000
	s_nop 0
	global_load_lds_dwordx4 v140, s[98:99]
	s_barrier
	s_waitcnt lgkmcnt(0)
	s_setprio 1
	v_mfma_f32_16x16x32_bf16 v[116:119], v[218:221], v[186:189], v[116:119]
	v_mfma_f32_16x16x32_bf16 v[108:111], v[226:229], v[186:189], v[108:111]
	v_mfma_f32_16x16x32_bf16 v[96:99], v[218:221], v[194:197], v[96:99]
	v_mfma_f32_16x16x32_bf16 v[88:91], v[226:229], v[194:197], v[88:91]
	v_mfma_f32_16x16x32_bf16 v[80:83], v[218:221], v[202:205], v[80:83]
	v_mfma_f32_16x16x32_bf16 v[72:75], v[226:229], v[202:205], v[72:75]
	v_mfma_f32_16x16x32_bf16 v[68:71], v[218:221], v[210:213], v[68:71]
	v_mfma_f32_16x16x32_bf16 v[64:67], v[226:229], v[210:213], v[64:67]
	v_mfma_f32_16x16x32_bf16 v[116:119], v[222:225], v[190:193], v[116:119]
	ds_read_b128 v[186:189], v155 offset:49152
	v_mfma_f32_16x16x32_bf16 v[108:111], v[230:233], v[190:193], v[108:111]
	v_mfma_f32_16x16x32_bf16 v[96:99], v[222:225], v[198:201], v[96:99]
	ds_read_b128 v[194:197], v155 offset:51200
	v_mfma_f32_16x16x32_bf16 v[88:91], v[230:233], v[198:201], v[88:91]
	v_mfma_f32_16x16x32_bf16 v[80:83], v[222:225], v[206:209], v[80:83]
	ds_read_b128 v[202:205], v155 offset:53248
	v_mfma_f32_16x16x32_bf16 v[72:75], v[230:233], v[206:209], v[72:75]
	v_mfma_f32_16x16x32_bf16 v[68:71], v[222:225], v[214:217], v[68:71]
	ds_read_b128 v[210:213], v155 offset:55296
	v_mfma_f32_16x16x32_bf16 v[64:67], v[230:233], v[214:217], v[64:67]
	s_setprio 0
	s_mov_b32 m0, s56
	s_add_u32 s100, s100, s10
	s_addc_u32 s101, s101, s11
	s_barrier
	ds_read_b128 v[190:193], v155 offset:50176
	ds_read_b128 v[198:201], v155 offset:52224
	ds_read_b128 v[206:209], v155 offset:54272
	ds_read_b128 v[214:217], v155 offset:56320
	global_load_lds_dwordx4 v134, s[100:101]
	s_mov_b32 m0, s57
	s_nop 0
	global_load_lds_dwordx4 v138, s[100:101]
	s_waitcnt vmcnt(8)
	s_barrier
	s_waitcnt lgkmcnt(0)
	s_setprio 1
	v_mfma_f32_16x16x32_bf16 v[60:63], v[158:161], v[186:189], v[60:63]
	v_mfma_f32_16x16x32_bf16 v[56:59], v[178:181], v[186:189], v[56:59]
	v_mfma_f32_16x16x32_bf16 v[52:55], v[158:161], v[194:197], v[52:55]
	v_mfma_f32_16x16x32_bf16 v[44:47], v[178:181], v[194:197], v[44:47]
	v_mfma_f32_16x16x32_bf16 v[36:39], v[158:161], v[202:205], v[36:39]
	v_mfma_f32_16x16x32_bf16 v[28:31], v[178:181], v[202:205], v[28:31]
	v_mfma_f32_16x16x32_bf16 v[20:23], v[158:161], v[210:213], v[20:23]
	v_mfma_f32_16x16x32_bf16 v[12:15], v[178:181], v[210:213], v[12:15]
	v_mfma_f32_16x16x32_bf16 v[60:63], v[174:177], v[190:193], v[60:63]
	v_mfma_f32_16x16x32_bf16 v[56:59], v[182:185], v[190:193], v[56:59]
	v_mfma_f32_16x16x32_bf16 v[52:55], v[174:177], v[198:201], v[52:55]
	v_mfma_f32_16x16x32_bf16 v[44:47], v[182:185], v[198:201], v[44:47]
	v_mfma_f32_16x16x32_bf16 v[36:39], v[174:177], v[206:209], v[36:39]
	v_mfma_f32_16x16x32_bf16 v[28:31], v[182:185], v[206:209], v[28:31]
	v_mfma_f32_16x16x32_bf16 v[20:23], v[174:177], v[214:217], v[20:23]
	v_mfma_f32_16x16x32_bf16 v[12:15], v[182:185], v[214:217], v[12:15]
	s_setprio 0
	s_barrier
	s_add_u32 s36, s36, 0x100080
	s_addc_u32 s37, s37, 0
	s_add_i32 s46, s46, s49
	s_mov_b32 m0, s46
	s_nop 0
	global_load_lds_dwordx4 v136, s[36:37]
	s_add_i32 m0, s46, 0x2000
	s_nop 0
	global_load_lds_dwordx4 v140, s[36:37]
	s_waitcnt vmcnt(6)
	s_barrier
	s_setprio 1
	v_mfma_f32_16x16x32_bf16 v[48:51], v[218:221], v[186:189], v[48:51]
	ds_read_b128 v[158:161], v154
	v_mfma_f32_16x16x32_bf16 v[40:43], v[226:229], v[186:189], v[40:43]
	v_mfma_f32_16x16x32_bf16 v[32:35], v[218:221], v[194:197], v[32:35]
	ds_read_b128 v[174:177], v154 offset:1024
	v_mfma_f32_16x16x32_bf16 v[24:27], v[226:229], v[194:197], v[24:27]
	v_mfma_f32_16x16x32_bf16 v[16:19], v[218:221], v[202:205], v[16:19]
	ds_read_b128 v[178:181], v154 offset:2048
	v_mfma_f32_16x16x32_bf16 v[8:11], v[226:229], v[202:205], v[8:11]
	v_mfma_f32_16x16x32_bf16 v[4:7], v[218:221], v[210:213], v[4:7]
	ds_read_b128 v[182:185], v154 offset:3072
	v_mfma_f32_16x16x32_bf16 v[0:3], v[226:229], v[210:213], v[0:3]
	v_mfma_f32_16x16x32_bf16 v[48:51], v[222:225], v[190:193], v[48:51]
	ds_read_b128 v[186:189], v155
	v_mfma_f32_16x16x32_bf16 v[40:43], v[230:233], v[190:193], v[40:43]
	v_mfma_f32_16x16x32_bf16 v[32:35], v[222:225], v[198:201], v[32:35]
	ds_read_b128 v[194:197], v155 offset:2048
	v_mfma_f32_16x16x32_bf16 v[24:27], v[230:233], v[198:201], v[24:27]
	v_mfma_f32_16x16x32_bf16 v[16:19], v[222:225], v[206:209], v[16:19]
	ds_read_b128 v[202:205], v155 offset:4096
	v_mfma_f32_16x16x32_bf16 v[8:11], v[230:233], v[206:209], v[8:11]
	v_mfma_f32_16x16x32_bf16 v[4:7], v[222:225], v[214:217], v[4:7]
	ds_read_b128 v[210:213], v155 offset:6144
	v_mfma_f32_16x16x32_bf16 v[0:3], v[230:233], v[214:217], v[0:3]
	s_setprio 0
	s_add_i32 s68, s68, 2
	s_add_u32 s28, s28, 0x100
	s_addc_u32 s29, s29, 0
	s_add_u32 s27, s27, 0x100
	s_addc_u32 s67, s67, 0
	s_cmp_gt_u32 s68, 61
	s_barrier
	s_cbranch_scc0 .LBB0_186
	s_waitcnt lgkmcnt(0)
	v_add_u32_e32 v157, s66, v131
	s_cmpk_gt_i32 s26, 0x17ff
	s_mov_b64 s[28:29], -1
	s_cbranch_scc0 .LBB0_189
	v_mov_b64_e32 v[150:151], s[20:21]
	v_mad_i64_i32 v[150:151], s[28:29], v157, s62, v[150:151]
	s_mov_b32 s27, s9
	v_lshl_add_u64 v[150:151], s[26:27], 1, v[150:151]
	v_lshl_add_u64 v[150:151], v[150:151], 0, s[12:13]
	s_mov_b64 s[28:29], 0
